# stack: HGRN chunk-state pass V tile hoist + in-proj epilogue head wait removed, on top of rotary-row hoist
# speedup vs baseline: 1.0389x; 1.0047x over previous
.LBB0_192:
	s_lshr_b32 s33, s10, 1
	s_cmp_eq_u32 s33, 10
	s_cselect_b64 s[4:5], -1, 0
	s_and_b32 s0, s10, 0x7c
	s_cmp_lg_u32 s0, 20
	s_cselect_b64 s[34:35], -1, 0
	s_and_b32 s1, s10, 0x76
	s_cmp_lg_u32 s1, 18
	s_cselect_b64 s[56:57], -1, 0
	s_cmp_eq_u32 s0, 8
	s_cselect_b64 s[10:11], -1, 0
	s_and_b32 s0, s22, 0x80
	v_or_b32_e32 v77, s0, v149
	s_lshl_b32 s0, s33, 10
	s_add_u32 s0, s38, s0
	s_addc_u32 s1, s39, 0
	s_add_u32 s12, s0, 0x10f000
	s_addc_u32 s13, s1, 0
	s_andn2_b64 vcc, exec, s[10:11]
	s_cbranch_vccnz .Lg0_nolb
	v_lshlrev_b32_e32 v2, 2, v77
	global_load_dwordx4 v[116:119], v2, s[12:13]
	global_load_dwordx4 v[120:123], v2, s[12:13] offset:64
	global_load_dwordx4 v[124:127], v2, s[12:13] offset:128
	global_load_dwordx4 v[128:131], v2, s[12:13] offset:192
